# prompt scans: one static s_setprio 1 for waves 0-3 (they carry more work per chunk than their SIMD partners), reset after the scans
# baseline (speedup 1.0000x reference)
; __device__ __forceinline__ int opaque_bid() { int t = blockIdx.x; asm volatile("" : "+s"(t)); return t; }
; template <bool ML>
; __device__ __forceinline__ void prompt_scan(const Params& p, unsigned char* smem, int job) {
;     ...
;             if (tid < 256) {
;                 load_block<ML>(p, val, b, p0, Lv, tid >> 4, tid & 15, vcol, h * 64, 1.f);
;                 store_cols(smem + L_VT, val, tid >> 4, tid & 15, nullptr);
;             }
; __device__ __forceinline__ void phase_scan(const Params& p, unsigned char* smem) {
;     ...
;     for (int j = opaque_bid(); j < 256; j += gridDim.x) { if (j < 128) { if (SC_MASK & 1) prompt_scan<false>(p, smem, j); } else { if (SC_MASK & 2) prompt_scan<true>(p, smem, j - 128); } }
;     if (SC_MASK & 4) for (int j = opaque_bid(); j < 256; j += gridDim.x) sample_ssd(p, smem, j);
;     if (SC_MASK & 8) for (int j = opaque_bid(); j < 1024; j += gridDim.x) sample_ml(p, smem, j);
; }
.LBB0_436:
	s_and_b64 vcc, exec, s[0:1]
	s_cbranch_vccz .LBB0_747
	v_readfirstlane_b32 s0, v151
	s_nop 3
	s_lshr_b32 s0, s0, 6
	s_cmp_lt_u32 s0, 4
	s_cbranch_scc0 .Lp2_prio_done
	s_setprio 1
.Lp2_prio_done:
	v_readlane_b32 s0, v254, 0
	s_mov_b32 s28, s0
	v_writelane_b32 v255, s82, 35
	s_cmpk_gt_i32 s28, 0xff
	s_nop 0
	v_writelane_b32 v255, s83, 36
	s_cbranch_scc1 .LBB0_663
	s_add_u32 s0, s82, 0x22680000
	s_addc_u32 s1, s83, 0
	v_writelane_b32 v255, s0, 37
	s_nop 1
	v_writelane_b32 v255, s1, 38
	s_add_u32 s0, s82, 0xec00000
	v_writelane_b32 v255, s0, 39
	s_addc_u32 s0, s83, 0
	v_writelane_b32 v255, s0, 40
	s_add_u32 s0, s82, 0x229f8000
	v_writelane_b32 v255, s0, 41
	s_addc_u32 s0, s83, 0
	v_writelane_b32 v255, s0, 42
	s_add_u32 s0, s82, 0x22b32800
	v_writelane_b32 v255, s0, 43
	s_addc_u32 s0, s83, 0
	v_writelane_b32 v255, s0, 44
	s_add_u32 s0, s82, 0xa200000
	v_writelane_b32 v255, s0, 45
	s_addc_u32 s0, s83, 0
	v_writelane_b32 v255, s0, 46
	s_add_u32 s0, s82, 0x228d0000
	v_writelane_b32 v255, s0, 47
	s_addc_u32 s0, s83, 0
	v_writelane_b32 v255, s0, 48
	s_nop 0
	v_readlane_b32 s0, v255, 31
	v_readlane_b32 s1, v255, 32
	s_add_u32 s0, s0, 0x481e000
	v_writelane_b32 v255, s0, 49
	s_addc_u32 s0, s1, 0
	v_writelane_b32 v255, s0, 50
	s_add_i32 s52, s28, 0xffffff80
	s_branch .LBB0_441

; __device__ __forceinline__ int opaque_bid() { int t = blockIdx.x; asm volatile("" : "+s"(t)); return t; }
; __device__ __forceinline__ void phase_scan(const Params& p, unsigned char* smem) {
;     ...
;     if (SC_MASK & 4) for (int j = opaque_bid(); j < 256; j += gridDim.x) sample_ssd(p, smem, j);
.LBB0_663:
	s_setprio 0
	v_readlane_b32 s42, v254, 0
	s_cmpk_gt_i32 s42, 0xff
	s_cbranch_scc1 .LBB0_712
	v_readlane_b32 s0, v255, 35
	v_readlane_b32 s1, v255, 36
	s_add_u32 s2, s0, 0xec00000
	s_addc_u32 s3, s1, 0
	s_add_u32 s38, s0, 0x22680000
	s_addc_u32 s39, s1, 0
	s_add_u32 s72, s0, 0xa200000
	s_addc_u32 s73, s1, 0
	v_readlane_b32 s4, v255, 31
	v_readlane_b32 s5, v255, 32
	s_add_u32 s74, s4, 0x543a080
	s_addc_u32 s75, s5, 0
	s_add_u32 s76, s0, 0x228d0000
	s_addc_u32 s77, s1, 0
	v_readlane_b32 s0, v254, 19
	v_readlane_b32 s4, v255, 27
	v_readlane_b32 s5, v255, 28
	s_add_u32 s78, s0, s4
	v_readlane_b32 s0, v254, 20
	s_addc_u32 s79, s0, s5
	s_bitcmp1_b32 s42, 0
	v_readlane_b32 s0, v254, 23
	s_cselect_b64 s[80:81], -1, 0
	s_add_u32 s82, s0, s4
	v_readlane_b32 s0, v254, 24
	s_addc_u32 s83, s0, s5
	v_readlane_b32 s0, v254, 25
	v_readlane_b32 s4, v255, 29
	v_readlane_b32 s5, v255, 30
	s_add_u32 s84, s0, s4
	v_readlane_b32 s0, v254, 30
	s_addc_u32 s85, s0, s5
	s_branch .LBB0_666
